# v20 plus: norm sample path (runtime-nsplit copy) loads the X row into a dead register so its wait merges with the split-K slice loads (one round trip instead of two)
# speedup vs baseline: 1.0016x; 1.0016x over previous
; __device__ __forceinline__ f32x4 sample_row_coop(const Frame& F, h16* X, const float* PART, int srow, int nsplit, LAS float* red, float& rs) {
;     ...
;     const int c = F.wave * 256 + F.lane * 4; h16x4* xp = (h16x4*)(X + (size_t)(TP + srow) * D + c); f32x4 v = __builtin_convertvector(*xp, f32x4);
;     if (nsplit > 0) { f32x4 s[7];
; #pragma unroll
;         for (int ks = 0; ks < 7; ++ks) s[ks] = ks < nsplit ? *(const f32x4*)(PART + ((size_t)ks * 128 + srow) * D + c) : (f32x4){0.f, 0.f, 0.f, 0.f};
.LBB0_2208:
	s_add_i32 s98, s6, 4
	s_mul_hi_i32 s99, s98, 0x48000
	s_mul_i32 s98, s98, 0x48000
	s_add_u32 s100, s56, s98
	s_addc_u32 s101, s57, s99
	v_lshl_add_u64 v[236:237], v[28:29], 2, s[100:101]
	global_load_dwordx4 v[224:227], v[236:237], off
	global_load_dwordx4 v[228:231], v[30:31], off
	s_add_u32 s100, s100, s89
	s_addc_u32 s101, s101, 0
	v_lshl_add_u64 v[238:239], v[28:29], 2, s[100:101]
	global_load_dwordx4 v[232:235], v[238:239], off
	v_lshl_add_u64 v[106:107], s[44:45], 0, v[100:101]
	global_load_dwordx2 v[240:241], v[106:107], off
	s_andn2_b64 vcc, exec, s[58:59]
	s_cbranch_vccnz .Lnorm_nosplit
	v_add_co_u32_e32 v0, vcc, 0xffa00000, v98
	v_mov_b32_e32 v8, 0
	s_nop 0
	v_addc_co_u32_e32 v1, vcc, -1, v99, vcc
	v_add_co_u32_e32 v4, vcc, 0xffb00000, v98
	v_mov_b32_e32 v12, 0
	s_nop 0
	v_addc_co_u32_e32 v5, vcc, -1, v99, vcc
	global_load_dwordx4 v[0:3], v[0:1], off
	s_nop 0
	global_load_dwordx4 v[4:7], v[4:5], off
	s_andn2_b64 vcc, exec, s[60:61]
	v_mov_b32_e32 v13, 0
	v_mov_b32_e32 v14, 0
	v_mov_b32_e32 v15, 0
	s_cbranch_vccnz .LBB0_2211
	v_add_co_u32_e32 v10, vcc, 0xffc00000, v98
	s_nop 1
	v_addc_co_u32_e32 v11, vcc, -1, v99, vcc
	global_load_dwordx4 v[12:15], v[10:11], off

; __device__ __forceinline__ f32x4 sample_row_coop(const Frame& F, h16* X, const float* PART, int srow, int nsplit, LAS float* red, float& rs) {
;     ...
;     if (nsplit > 0) { f32x4 s[7];
; #pragma unroll
;         for (int ks = 0; ks < 7; ++ks) s[ks] = ks < nsplit ? *(const f32x4*)(PART + ((size_t)ks * 128 + srow) * D + c) : (f32x4){0.f, 0.f, 0.f, 0.f};
;         v += ((s[0] + s[1]) + (s[2] + s[3])) + ((s[4] + s[5]) + s[6]); *xp = __builtin_convertvector(v, h16x4); }
.LBB0_2219:
	s_waitcnt vmcnt(0)
	v_cvt_f32_f16_e32 v102, v240
	v_cvt_f32_f16_e32 v104, v241
	v_cvt_f32_f16_sdwa v105, v241 dst_sel:DWORD dst_unused:UNUSED_PAD src0_sel:WORD_1
	v_cvt_f32_f16_sdwa v103, v240 dst_sel:DWORD dst_unused:UNUSED_PAD src0_sel:WORD_1
	v_pk_add_f32 v[2:3], v[2:3], v[6:7]
	v_pk_add_f32 v[0:1], v[0:1], v[4:5]
	v_pk_add_f32 v[4:5], v[12:13], v[8:9]
	v_pk_add_f32 v[6:7], v[14:15], v[10:11]
	v_pk_add_f32 v[0:1], v[0:1], v[4:5]
	v_pk_add_f32 v[2:3], v[2:3], v[6:7]
	v_pk_add_f32 v[4:5], v[22:23], v[18:19]
	v_pk_add_f32 v[6:7], v[20:21], v[16:17]
	v_pk_add_f32 v[4:5], v[4:5], v[26:27]
	v_pk_add_f32 v[6:7], v[6:7], v[24:25]
	v_pk_add_f32 v[2:3], v[2:3], v[4:5]
	v_pk_add_f32 v[0:1], v[0:1], v[6:7]
	v_pk_add_f32 v[104:105], v[2:3], v[104:105]
	v_pk_add_f32 v[102:103], v[0:1], v[102:103]
	v_cvt_pk_f16_f32 v1, v104, v105
	v_cvt_pk_f16_f32 v0, v102, v103
	global_store_dwordx2 v[106:107], v[0:1], off

; __device__ __forceinline__ f32x4 sample_row_coop(const Frame& F, h16* X, const float* PART, int srow, int nsplit, LAS float* red, float& rs) {
;     ...
;     const int c = F.wave * 256 + F.lane * 4; h16x4* xp = (h16x4*)(X + (size_t)(TP + srow) * D + c); f32x4 v = __builtin_convertvector(*xp, f32x4);
;     if (nsplit > 0) { f32x4 s[7];
; #pragma unroll
;         for (int ks = 0; ks < 7; ++ks) s[ks] = ks < nsplit ? *(const f32x4*)(PART + ((size_t)ks * 128 + srow) * D + c) : (f32x4){0.f, 0.f, 0.f, 0.f};
;         v += ((s[0] + s[1]) + (s[2] + s[3])) + ((s[4] + s[5]) + s[6]); *xp = __builtin_convertvector(v, h16x4); }
;     const float ss = wave_sum((v[0] * v[0] + v[1] * v[1]) + (v[2] * v[2] + v[3] * v[3]));
.Lnorm_nosplit:
	s_waitcnt vmcnt(0)
	v_cvt_f32_f16_e32 v102, v240
	v_cvt_f32_f16_e32 v104, v241
	v_cvt_f32_f16_sdwa v105, v241 dst_sel:DWORD dst_unused:UNUSED_PAD src0_sel:WORD_1
	v_cvt_f32_f16_sdwa v103, v240 dst_sel:DWORD dst_unused:UNUSED_PAD src0_sel:WORD_1
	s_branch .LBB0_2220
